# gla output pass: the 32 per-token q/k loads of a sub-chunk issued together
# speedup vs baseline: 1.1094x; 1.0074x over previous
.LBB0_40:
	s_or_b64 exec, exec, s[0:1]
	s_and_saveexec_b64 s[0:1], s[8:9]
	ds_write_b32 v169, v1 offset:6656
	s_or_b64 exec, exec, s[0:1]
	s_waitcnt lgkmcnt(0)
	s_barrier
	ds_read_b128 v[66:69], v168
	ds_read_b128 v[70:73], v168 offset:16
	ds_read_b128 v[74:77], v168 offset:32
	ds_read_b128 v[78:81], v168 offset:48
	s_mov_b32 s2, 0xbfb8aa3b
	s_waitcnt lgkmcnt(3)
	v_mov_b32_e32 v82, v66
	s_waitcnt lgkmcnt(2)
	v_mov_b32_e32 v83, v70
	v_mov_b32_e32 v70, v67
	s_waitcnt vmcnt(30)
	v_pk_mul_f32 v[66:67], v[100:101], v[70:71]
	v_mov_b32_e32 v70, v68
	v_pk_fma_f32 v[66:67], v[98:99], v[82:83], v[66:67]
	v_mov_b32_e32 v71, v72
	s_waitcnt vmcnt(29)
	v_pk_fma_f32 v[66:67], v[102:103], v[70:71], v[66:67]
	v_mov_b32_e32 v72, v69
	s_waitcnt vmcnt(22)
	v_pk_fma_f32 v[66:67], v[110:111], v[72:73], v[66:67]
	s_mov_b32 s33, 0x800000
	s_waitcnt vmcnt(18)
	v_add_f32_e32 v0, v165, v66
	v_add_f32_e32 v0, v0, v67
	s_waitcnt lgkmcnt(0)
	v_mov_b32_e32 v67, v78
	v_mov_b32_e32 v78, v75
	v_mov_b32_e32 v66, v74
	v_pk_mul_f32 v[68:69], v[106:107], v[78:79]
	s_mov_b32 s3, 0x3f317217
	v_pk_fma_f32 v[66:67], v[104:105], v[66:67], v[68:69]
	v_mov_b32_e32 v68, v76
	v_mov_b32_e32 v69, v80
	v_pk_fma_f32 v[66:67], v[108:109], v[68:69], v[66:67]
	v_mov_b32_e32 v80, v77
	v_pk_fma_f32 v[66:67], v[112:113], v[80:81], v[66:67]
	ds_read_b128 v[68:71], v168 offset:64
	ds_read_b128 v[72:75], v168 offset:80
	v_add_f32_e32 v0, v0, v66
	v_add_f32_e32 v0, v0, v67
	v_min_f32_e32 v66, 0, v0
	v_mul_f32_e64 v0, |v0|, s2
	v_exp_f32_e32 v0, v0
	s_mov_b32 s69, 0x7f800000
	s_waitcnt lgkmcnt(0)
	v_mov_b32_e32 v77, v72
	v_mov_b32_e32 v72, v69
	v_add_f32_e32 v0, 1.0, v0
	v_cmp_gt_f32_e32 vcc, s33, v0
	v_mov_b32_e32 v76, v68
	v_pk_mul_f32 v[68:69], v[100:101], v[72:73]
	v_cndmask_b32_e64 v67, 0, 32, vcc
	v_ldexp_f32 v0, v0, v67
	v_log_f32_e32 v0, v0
	v_pk_fma_f32 v[68:69], v[98:99], v[76:77], v[68:69]
	v_mov_b32_e32 v72, v70
	v_mov_b32_e32 v73, v74
	v_mul_f32_e32 v67, 0x3f317217, v0
	v_fma_f32 v67, v0, s3, -v67
	v_fmac_f32_e32 v67, 0x3377d1cf, v0
	v_fmac_f32_e32 v67, 0x3f317217, v0
	v_cmp_lt_f32_e64 s[0:1], |v0|, s69
	v_pk_fma_f32 v[68:69], v[102:103], v[72:73], v[68:69]
	v_mov_b32_e32 v74, v71
	v_cndmask_b32_e64 v0, v0, v67, s[0:1]
	v_cndmask_b32_e32 v67, 0, v223, vcc
	v_sub_f32_e32 v0, v0, v67
	v_sub_f32_e32 v0, v66, v0
	v_pk_fma_f32 v[68:69], v[110:111], v[74:75], v[68:69]
	v_fma_f32 v66, v0, s90, 0
	v_add_f32_e32 v0, v165, v68
	v_add_f32_e32 v0, v0, v69
	ds_read_b128 v[68:71], v168 offset:96
	ds_read_b128 v[72:75], v168 offset:112
	s_waitcnt lgkmcnt(1)
	v_mov_b32_e32 v76, v68
	s_waitcnt lgkmcnt(0)
	v_mov_b32_e32 v77, v72
	v_mov_b32_e32 v72, v69
	v_pk_mul_f32 v[68:69], v[106:107], v[72:73]
	v_mov_b32_e32 v72, v70
	v_pk_fma_f32 v[68:69], v[104:105], v[76:77], v[68:69]
	v_mov_b32_e32 v73, v74
	v_pk_fma_f32 v[68:69], v[108:109], v[72:73], v[68:69]
	v_mov_b32_e32 v74, v71
	v_pk_fma_f32 v[68:69], v[112:113], v[74:75], v[68:69]
	s_nop 0
	v_add_f32_e32 v0, v0, v68
	v_add_f32_e32 v0, v0, v69
	v_min_f32_e32 v67, 0, v0
	v_mul_f32_e64 v0, |v0|, s2
	v_exp_f32_e32 v0, v0
	s_nop 0
	v_add_f32_e32 v0, 1.0, v0
	v_cmp_gt_f32_e32 vcc, s33, v0
	s_nop 1
	v_cndmask_b32_e64 v68, 0, 32, vcc
	v_ldexp_f32 v0, v0, v68
	v_log_f32_e32 v0, v0
	s_nop 0
	v_mul_f32_e32 v68, 0x3f317217, v0
	v_fma_f32 v68, v0, s3, -v68
	v_fmac_f32_e32 v68, 0x3377d1cf, v0
	v_fmac_f32_e32 v68, 0x3f317217, v0
	v_cmp_lt_f32_e64 s[0:1], |v0|, s69
	s_nop 1
	v_cndmask_b32_e64 v0, v0, v68, s[0:1]
	v_cndmask_b32_e32 v68, 0, v223, vcc
	v_sub_f32_e32 v0, v0, v68
	ds_read_b128 v[68:71], v168 offset:128
	ds_read_b128 v[72:75], v168 offset:144
	v_sub_f32_e32 v0, v67, v0
	v_fmamk_f32 v67, v0, 0x3d800000, v66
	s_waitcnt lgkmcnt(1)
	v_mov_b32_e32 v76, v68
	s_waitcnt lgkmcnt(0)
	v_mov_b32_e32 v77, v72
	v_mov_b32_e32 v72, v69
	v_pk_mul_f32 v[68:69], v[100:101], v[72:73]
	v_mov_b32_e32 v72, v70
	v_pk_fma_f32 v[68:69], v[98:99], v[76:77], v[68:69]
	v_mov_b32_e32 v73, v74
	v_pk_fma_f32 v[68:69], v[102:103], v[72:73], v[68:69]
	v_mov_b32_e32 v74, v71
	v_pk_fma_f32 v[68:69], v[110:111], v[74:75], v[68:69]
	s_nop 0
	v_add_f32_e32 v0, v165, v68
	v_add_f32_e32 v0, v0, v69
	ds_read_b128 v[68:71], v168 offset:160
	ds_read_b128 v[72:75], v168 offset:176
	s_waitcnt lgkmcnt(1)
	v_mov_b32_e32 v76, v68
	s_waitcnt lgkmcnt(0)
	v_mov_b32_e32 v77, v72
	v_mov_b32_e32 v72, v69
	v_pk_mul_f32 v[68:69], v[106:107], v[72:73]
	v_mov_b32_e32 v72, v70
	v_pk_fma_f32 v[68:69], v[104:105], v[76:77], v[68:69]
	v_mov_b32_e32 v73, v74
	v_pk_fma_f32 v[68:69], v[108:109], v[72:73], v[68:69]
	v_mov_b32_e32 v74, v71
	v_pk_fma_f32 v[68:69], v[112:113], v[74:75], v[68:69]
	ds_read_b128 v[70:73], v168 offset:192
	ds_read_b128 v[74:77], v168 offset:208
	v_add_f32_e32 v0, v0, v68
	v_add_f32_e32 v0, v0, v69
	v_min_f32_e32 v68, 0, v0
	v_mul_f32_e64 v0, |v0|, s2
	v_exp_f32_e32 v0, v0
	s_waitcnt lgkmcnt(0)
	v_mov_b32_e32 v79, v74
	v_mov_b32_e32 v74, v71
	v_mov_b32_e32 v78, v70
	v_add_f32_e32 v0, 1.0, v0
	v_cmp_gt_f32_e32 vcc, s33, v0
	v_pk_mul_f32 v[70:71], v[100:101], v[74:75]
	v_mov_b32_e32 v74, v72
	v_cndmask_b32_e64 v69, 0, 32, vcc
	v_ldexp_f32 v0, v0, v69
	v_log_f32_e32 v0, v0
	v_pk_fma_f32 v[70:71], v[98:99], v[78:79], v[70:71]
	v_mov_b32_e32 v75, v76
	v_pk_fma_f32 v[70:71], v[102:103], v[74:75], v[70:71]
	v_mul_f32_e32 v69, 0x3f317217, v0
	v_fma_f32 v69, v0, s3, -v69
	v_fmac_f32_e32 v69, 0x3377d1cf, v0
	v_fmac_f32_e32 v69, 0x3f317217, v0
	v_cmp_lt_f32_e64 s[0:1], |v0|, s69
	v_mov_b32_e32 v76, v73
	v_pk_fma_f32 v[70:71], v[110:111], v[76:77], v[70:71]
	v_cndmask_b32_e64 v0, v0, v69, s[0:1]
	v_cndmask_b32_e32 v69, 0, v223, vcc
	v_sub_f32_e32 v0, v0, v69
	v_sub_f32_e32 v0, v68, v0
	v_fmamk_f32 v68, v0, 0x3d800000, v67
	v_add_f32_e32 v0, v165, v70
	v_add_f32_e32 v0, v0, v71
	ds_read_b128 v[70:73], v168 offset:224
	ds_read_b128 v[74:77], v168 offset:240
	s_waitcnt lgkmcnt(1)
	v_mov_b32_e32 v78, v70
	s_waitcnt lgkmcnt(0)
	v_mov_b32_e32 v79, v74
	v_mov_b32_e32 v74, v71
	v_pk_mul_f32 v[70:71], v[106:107], v[74:75]
	v_mov_b32_e32 v74, v72
	v_pk_fma_f32 v[70:71], v[104:105], v[78:79], v[70:71]
	v_mov_b32_e32 v75, v76
	v_pk_fma_f32 v[70:71], v[108:109], v[74:75], v[70:71]
	v_mov_b32_e32 v76, v73
	v_pk_fma_f32 v[70:71], v[112:113], v[76:77], v[70:71]
	s_nop 0
	v_add_f32_e32 v0, v0, v70
	v_add_f32_e32 v0, v0, v71
	v_min_f32_e32 v69, 0, v0
	v_mul_f32_e64 v0, |v0|, s2
	v_exp_f32_e32 v0, v0
	s_nop 0
	v_add_f32_e32 v0, 1.0, v0
	v_cmp_gt_f32_e32 vcc, s33, v0
	s_nop 1
	v_cndmask_b32_e64 v70, 0, 32, vcc
	v_ldexp_f32 v0, v0, v70
	v_log_f32_e32 v0, v0
	s_nop 0
	v_mul_f32_e32 v70, 0x3f317217, v0
	v_fma_f32 v70, v0, s3, -v70
	v_fmac_f32_e32 v70, 0x3377d1cf, v0
	v_fmac_f32_e32 v70, 0x3f317217, v0
	v_cmp_lt_f32_e64 s[0:1], |v0|, s69
	s_nop 1
	v_cndmask_b32_e64 v0, v0, v70, s[0:1]
	v_cndmask_b32_e32 v70, 0, v223, vcc
	v_sub_f32_e32 v0, v0, v70
	ds_read_b128 v[70:73], v168 offset:256
	ds_read_b128 v[74:77], v168 offset:272
	v_sub_f32_e32 v0, v69, v0
	v_fmamk_f32 v69, v0, 0x3d800000, v68
	s_waitcnt lgkmcnt(1)
	v_mov_b32_e32 v78, v70
	s_waitcnt lgkmcnt(0)
	v_mov_b32_e32 v79, v74
	v_mov_b32_e32 v74, v71
	v_pk_mul_f32 v[70:71], v[100:101], v[74:75]
	v_mov_b32_e32 v74, v72
	v_pk_fma_f32 v[70:71], v[98:99], v[78:79], v[70:71]
	v_mov_b32_e32 v75, v76
	v_pk_fma_f32 v[70:71], v[102:103], v[74:75], v[70:71]
	v_mov_b32_e32 v76, v73
	v_pk_fma_f32 v[70:71], v[110:111], v[76:77], v[70:71]
	s_nop 0
	v_add_f32_e32 v0, v165, v70
	v_add_f32_e32 v0, v0, v71
	ds_read_b128 v[70:73], v168 offset:288
	ds_read_b128 v[74:77], v168 offset:304
	s_waitcnt lgkmcnt(1)
	v_mov_b32_e32 v78, v70
	s_waitcnt lgkmcnt(0)
	v_mov_b32_e32 v79, v74
	v_mov_b32_e32 v74, v71
	v_pk_mul_f32 v[70:71], v[106:107], v[74:75]
	v_mov_b32_e32 v74, v72
	v_pk_fma_f32 v[70:71], v[104:105], v[78:79], v[70:71]
	v_mov_b32_e32 v75, v76
	v_pk_fma_f32 v[70:71], v[108:109], v[74:75], v[70:71]
	v_mov_b32_e32 v76, v73
	v_pk_fma_f32 v[70:71], v[112:113], v[76:77], v[70:71]
	ds_read_b128 v[72:75], v168 offset:320
	ds_read_b128 v[76:79], v168 offset:336
	v_add_f32_e32 v0, v0, v70
	v_add_f32_e32 v0, v0, v71
	v_min_f32_e32 v70, 0, v0
	v_mul_f32_e64 v0, |v0|, s2
	v_exp_f32_e32 v0, v0
	s_waitcnt lgkmcnt(0)
	v_mov_b32_e32 v81, v76
	v_mov_b32_e32 v76, v73
	v_mov_b32_e32 v80, v72
	v_add_f32_e32 v0, 1.0, v0
	v_cmp_gt_f32_e32 vcc, s33, v0
	v_pk_mul_f32 v[72:73], v[100:101], v[76:77]
	v_mov_b32_e32 v76, v74
	v_cndmask_b32_e64 v71, 0, 32, vcc
	v_ldexp_f32 v0, v0, v71
	v_log_f32_e32 v0, v0
	v_pk_fma_f32 v[72:73], v[98:99], v[80:81], v[72:73]
	v_mov_b32_e32 v77, v78
	v_pk_fma_f32 v[72:73], v[102:103], v[76:77], v[72:73]
	v_mul_f32_e32 v71, 0x3f317217, v0
	v_fma_f32 v71, v0, s3, -v71
	v_fmac_f32_e32 v71, 0x3377d1cf, v0
	v_fmac_f32_e32 v71, 0x3f317217, v0
	v_cmp_lt_f32_e64 s[0:1], |v0|, s69
	v_mov_b32_e32 v78, v75
	v_pk_fma_f32 v[72:73], v[110:111], v[78:79], v[72:73]
	v_cndmask_b32_e64 v0, v0, v71, s[0:1]
	v_cndmask_b32_e32 v71, 0, v223, vcc
	v_sub_f32_e32 v0, v0, v71
	v_sub_f32_e32 v0, v70, v0
	v_fmamk_f32 v70, v0, 0x3d800000, v69
	v_add_f32_e32 v0, v165, v72
	v_add_f32_e32 v0, v0, v73
	ds_read_b128 v[72:75], v168 offset:352
	ds_read_b128 v[76:79], v168 offset:368
	s_waitcnt lgkmcnt(1)
	v_mov_b32_e32 v80, v72
	s_waitcnt lgkmcnt(0)
	v_mov_b32_e32 v81, v76
	v_mov_b32_e32 v76, v73
	v_pk_mul_f32 v[72:73], v[106:107], v[76:77]
	v_mov_b32_e32 v76, v74
	v_pk_fma_f32 v[72:73], v[104:105], v[80:81], v[72:73]
	v_mov_b32_e32 v77, v78
	v_pk_fma_f32 v[72:73], v[108:109], v[76:77], v[72:73]
	v_mov_b32_e32 v78, v75
	v_pk_fma_f32 v[72:73], v[112:113], v[78:79], v[72:73]
	s_nop 0
	v_add_f32_e32 v0, v0, v72
	v_add_f32_e32 v0, v0, v73
	v_min_f32_e32 v71, 0, v0
	v_mul_f32_e64 v0, |v0|, s2
	v_exp_f32_e32 v0, v0
	s_nop 0
	v_add_f32_e32 v0, 1.0, v0
	v_cmp_gt_f32_e32 vcc, s33, v0
	s_nop 1
	v_cndmask_b32_e64 v72, 0, 32, vcc
	v_ldexp_f32 v0, v0, v72
	v_log_f32_e32 v0, v0
	s_nop 0
	v_mul_f32_e32 v72, 0x3f317217, v0
	v_fma_f32 v72, v0, s3, -v72
	v_fmac_f32_e32 v72, 0x3377d1cf, v0
	v_fmac_f32_e32 v72, 0x3f317217, v0
	v_cmp_lt_f32_e64 s[0:1], |v0|, s69
	s_nop 1
	v_cndmask_b32_e64 v0, v0, v72, s[0:1]
	v_cndmask_b32_e32 v72, 0, v223, vcc
	v_sub_f32_e32 v0, v0, v72
	ds_read_b128 v[72:75], v168 offset:384
	ds_read_b128 v[76:79], v168 offset:400
	v_sub_f32_e32 v0, v71, v0
	v_fmamk_f32 v71, v0, 0x3d800000, v70
	s_waitcnt lgkmcnt(1)
	v_mov_b32_e32 v80, v72
	s_waitcnt lgkmcnt(0)
	v_mov_b32_e32 v81, v76
	v_mov_b32_e32 v76, v73
	v_pk_mul_f32 v[72:73], v[100:101], v[76:77]
	v_mov_b32_e32 v76, v74
	v_pk_fma_f32 v[72:73], v[98:99], v[80:81], v[72:73]
	v_mov_b32_e32 v77, v78
	v_pk_fma_f32 v[72:73], v[102:103], v[76:77], v[72:73]
	v_mov_b32_e32 v78, v75
	v_pk_fma_f32 v[72:73], v[110:111], v[78:79], v[72:73]
	s_nop 0
	v_add_f32_e32 v0, v165, v72
	v_add_f32_e32 v0, v0, v73
	ds_read_b128 v[72:75], v168 offset:416
	ds_read_b128 v[76:79], v168 offset:432
	s_waitcnt lgkmcnt(1)
	v_mov_b32_e32 v80, v72
	s_waitcnt lgkmcnt(0)
	v_mov_b32_e32 v81, v76
	v_mov_b32_e32 v76, v73
	v_pk_mul_f32 v[72:73], v[106:107], v[76:77]
	v_mov_b32_e32 v76, v74
	v_pk_fma_f32 v[72:73], v[104:105], v[80:81], v[72:73]
	v_mov_b32_e32 v77, v78
	v_pk_fma_f32 v[72:73], v[108:109], v[76:77], v[72:73]
	v_mov_b32_e32 v78, v75
	v_pk_fma_f32 v[72:73], v[112:113], v[78:79], v[72:73]
	ds_read_b128 v[74:77], v168 offset:448
	ds_read_b128 v[78:81], v168 offset:464
	v_add_f32_e32 v0, v0, v72
	v_add_f32_e32 v0, v0, v73
	v_min_f32_e32 v72, 0, v0
	v_mul_f32_e64 v0, |v0|, s2
	v_exp_f32_e32 v0, v0
	s_waitcnt lgkmcnt(0)
	v_mov_b32_e32 v83, v78
	v_mov_b32_e32 v78, v75
	v_mov_b32_e32 v82, v74
	v_add_f32_e32 v0, 1.0, v0
	v_cmp_gt_f32_e32 vcc, s33, v0
	v_pk_mul_f32 v[74:75], v[100:101], v[78:79]
	v_mov_b32_e32 v78, v76
	v_cndmask_b32_e64 v73, 0, 32, vcc
	v_ldexp_f32 v0, v0, v73
	v_log_f32_e32 v0, v0
	v_pk_fma_f32 v[74:75], v[98:99], v[82:83], v[74:75]
	v_mov_b32_e32 v79, v80
	v_pk_fma_f32 v[74:75], v[102:103], v[78:79], v[74:75]
	v_mul_f32_e32 v73, 0x3f317217, v0
	v_fma_f32 v73, v0, s3, -v73
	v_fmac_f32_e32 v73, 0x3377d1cf, v0
	v_fmac_f32_e32 v73, 0x3f317217, v0
	v_cmp_lt_f32_e64 s[0:1], |v0|, s69
	v_mov_b32_e32 v80, v77
	v_pk_fma_f32 v[74:75], v[110:111], v[80:81], v[74:75]
	v_cndmask_b32_e64 v0, v0, v73, s[0:1]
	v_cndmask_b32_e32 v73, 0, v223, vcc
	v_sub_f32_e32 v0, v0, v73
	v_sub_f32_e32 v0, v72, v0
	v_fmamk_f32 v73, v0, 0x3d800000, v71
	v_add_f32_e32 v0, v165, v74
	v_add_f32_e32 v0, v0, v75
	ds_read_b128 v[74:77], v168 offset:480
	ds_read_b128 v[78:81], v168 offset:496
	s_waitcnt lgkmcnt(1)
	v_mov_b32_e32 v82, v74
	s_waitcnt lgkmcnt(0)
	v_mov_b32_e32 v83, v78
	v_mov_b32_e32 v78, v75
	v_pk_mul_f32 v[74:75], v[106:107], v[78:79]
	v_mov_b32_e32 v78, v76
	v_pk_fma_f32 v[74:75], v[104:105], v[82:83], v[74:75]
	v_mov_b32_e32 v79, v80
	v_pk_fma_f32 v[74:75], v[108:109], v[78:79], v[74:75]
	v_mov_b32_e32 v80, v77
	v_pk_fma_f32 v[74:75], v[112:113], v[80:81], v[74:75]
	ds_read_b128 v[76:79], v168 offset:512
	ds_read_b128 v[80:83], v168 offset:528
	v_add_f32_e32 v0, v0, v74
	v_add_f32_e32 v0, v0, v75
	v_min_f32_e32 v72, 0, v0
	v_mul_f32_e64 v0, |v0|, s2
	v_exp_f32_e32 v0, v0
	s_waitcnt lgkmcnt(0)
	v_mov_b32_e32 v85, v80
	v_mov_b32_e32 v80, v77
	v_mov_b32_e32 v84, v76
	v_add_f32_e32 v0, 1.0, v0
	v_cmp_gt_f32_e32 vcc, s33, v0
	v_pk_mul_f32 v[76:77], v[100:101], v[80:81]
	v_mov_b32_e32 v80, v78
	v_cndmask_b32_e64 v74, 0, 32, vcc
	v_ldexp_f32 v0, v0, v74
	v_log_f32_e32 v0, v0
	v_pk_fma_f32 v[76:77], v[98:99], v[84:85], v[76:77]
	v_mov_b32_e32 v81, v82
	v_pk_fma_f32 v[76:77], v[102:103], v[80:81], v[76:77]
	v_mul_f32_e32 v74, 0x3f317217, v0
	v_fma_f32 v74, v0, s3, -v74
	v_fmac_f32_e32 v74, 0x3377d1cf, v0
	v_fmac_f32_e32 v74, 0x3f317217, v0
	v_cmp_lt_f32_e64 s[0:1], |v0|, s69
	v_mov_b32_e32 v82, v79
	v_pk_fma_f32 v[76:77], v[110:111], v[82:83], v[76:77]
	v_cndmask_b32_e64 v0, v0, v74, s[0:1]
	v_cndmask_b32_e32 v74, 0, v223, vcc
	v_sub_f32_e32 v0, v0, v74
	v_sub_f32_e32 v0, v72, v0
	v_fmamk_f32 v75, v0, 0x3d800000, v73
	v_add_f32_e32 v0, v165, v76
	v_add_f32_e32 v0, v0, v77
	ds_read_b128 v[76:79], v168 offset:544
	ds_read_b128 v[80:83], v168 offset:560
	s_waitcnt lgkmcnt(1)
	v_mov_b32_e32 v84, v76
	s_waitcnt lgkmcnt(0)
	v_mov_b32_e32 v85, v80
	v_mov_b32_e32 v80, v77
	v_pk_mul_f32 v[76:77], v[106:107], v[80:81]
	v_mov_b32_e32 v80, v78
	v_pk_fma_f32 v[76:77], v[104:105], v[84:85], v[76:77]
	v_mov_b32_e32 v81, v82
	v_pk_fma_f32 v[76:77], v[108:109], v[80:81], v[76:77]
	v_mov_b32_e32 v82, v79
	v_pk_fma_f32 v[76:77], v[112:113], v[82:83], v[76:77]
	ds_read_b128 v[78:81], v168 offset:576
	ds_read_b128 v[82:85], v168 offset:592
	v_add_f32_e32 v0, v0, v76
	v_add_f32_e32 v0, v0, v77
	v_min_f32_e32 v72, 0, v0
	v_mul_f32_e64 v0, |v0|, s2
	v_exp_f32_e32 v0, v0
	s_waitcnt lgkmcnt(0)
	v_mov_b32_e32 v87, v82
	v_mov_b32_e32 v82, v79
	v_mov_b32_e32 v86, v78
	v_add_f32_e32 v0, 1.0, v0
	v_cmp_gt_f32_e32 vcc, s33, v0
	v_pk_mul_f32 v[78:79], v[100:101], v[82:83]
	v_mov_b32_e32 v82, v80
	v_cndmask_b32_e64 v74, 0, 32, vcc
	v_ldexp_f32 v0, v0, v74
	v_log_f32_e32 v0, v0
	v_pk_fma_f32 v[78:79], v[98:99], v[86:87], v[78:79]
	v_mov_b32_e32 v83, v84
	v_pk_fma_f32 v[78:79], v[102:103], v[82:83], v[78:79]
	v_mul_f32_e32 v74, 0x3f317217, v0
	v_fma_f32 v74, v0, s3, -v74
	v_fmac_f32_e32 v74, 0x3377d1cf, v0
	v_fmac_f32_e32 v74, 0x3f317217, v0
	v_cmp_lt_f32_e64 s[0:1], |v0|, s69
	v_mov_b32_e32 v84, v81
	v_pk_fma_f32 v[78:79], v[110:111], v[84:85], v[78:79]
	v_cndmask_b32_e64 v0, v0, v74, s[0:1]
	v_cndmask_b32_e32 v74, 0, v223, vcc
	v_sub_f32_e32 v0, v0, v74
	v_sub_f32_e32 v0, v72, v0
	v_fmamk_f32 v76, v0, 0x3d800000, v75
	v_add_f32_e32 v0, v165, v78
	v_add_f32_e32 v0, v0, v79
	ds_read_b128 v[78:81], v168 offset:608
	ds_read_b128 v[82:85], v168 offset:624
	s_waitcnt lgkmcnt(1)
	v_mov_b32_e32 v86, v78
	s_waitcnt lgkmcnt(0)
	v_mov_b32_e32 v87, v82
	v_mov_b32_e32 v82, v79
	v_pk_mul_f32 v[78:79], v[106:107], v[82:83]
	v_mov_b32_e32 v82, v80
	v_pk_fma_f32 v[78:79], v[104:105], v[86:87], v[78:79]
	v_mov_b32_e32 v83, v84
	v_pk_fma_f32 v[78:79], v[108:109], v[82:83], v[78:79]
	v_mov_b32_e32 v84, v81
	v_pk_fma_f32 v[78:79], v[112:113], v[84:85], v[78:79]
	s_nop 0
	v_add_f32_e32 v0, v0, v78
	v_add_f32_e32 v0, v0, v79
	v_min_f32_e32 v72, 0, v0
	v_mul_f32_e64 v0, |v0|, s2
	v_exp_f32_e32 v0, v0
	ds_read_b128 v[78:81], v168 offset:640
	ds_read_b128 v[82:85], v168 offset:656
	v_add_f32_e32 v0, 1.0, v0
	v_cmp_gt_f32_e32 vcc, s33, v0
	s_waitcnt lgkmcnt(0)
	v_mov_b32_e32 v87, v82
	v_mov_b32_e32 v82, v79
	v_cndmask_b32_e64 v74, 0, 32, vcc
	v_ldexp_f32 v0, v0, v74
	v_log_f32_e32 v0, v0
	v_mov_b32_e32 v86, v78
	v_pk_mul_f32 v[78:79], v[100:101], v[82:83]
	v_mov_b32_e32 v82, v80
	v_mul_f32_e32 v74, 0x3f317217, v0
	v_fma_f32 v74, v0, s3, -v74
	v_fmac_f32_e32 v74, 0x3377d1cf, v0
	v_fmac_f32_e32 v74, 0x3f317217, v0
	v_cmp_lt_f32_e64 s[0:1], |v0|, s69
	v_pk_fma_f32 v[78:79], v[98:99], v[86:87], v[78:79]
	v_mov_b32_e32 v83, v84
	v_cndmask_b32_e64 v0, v0, v74, s[0:1]
	v_cndmask_b32_e32 v74, 0, v223, vcc
	v_sub_f32_e32 v0, v0, v74
	v_pk_fma_f32 v[78:79], v[102:103], v[82:83], v[78:79]
	v_mov_b32_e32 v84, v81
	v_sub_f32_e32 v0, v72, v0
	v_pk_fma_f32 v[78:79], v[110:111], v[84:85], v[78:79]
	v_fmamk_f32 v72, v0, 0x3d800000, v76
	v_add_f32_e32 v0, v165, v78
	v_add_f32_e32 v0, v0, v79
	ds_read_b128 v[78:81], v168 offset:672
	ds_read_b128 v[82:85], v168 offset:688
	s_waitcnt lgkmcnt(1)
	v_mov_b32_e32 v86, v78
	s_waitcnt lgkmcnt(0)
	v_mov_b32_e32 v87, v82
	v_mov_b32_e32 v82, v79
	v_pk_mul_f32 v[78:79], v[106:107], v[82:83]
	v_mov_b32_e32 v82, v80
	v_pk_fma_f32 v[78:79], v[104:105], v[86:87], v[78:79]
	v_mov_b32_e32 v83, v84
	v_pk_fma_f32 v[78:79], v[108:109], v[82:83], v[78:79]
	v_mov_b32_e32 v84, v81
	v_pk_fma_f32 v[78:79], v[112:113], v[84:85], v[78:79]
	s_nop 0
	v_add_f32_e32 v0, v0, v78
	v_add_f32_e32 v0, v0, v79
	v_min_f32_e32 v74, 0, v0
	v_mul_f32_e64 v0, |v0|, s2
	v_exp_f32_e32 v0, v0
	ds_read_b128 v[78:81], v168 offset:704
	ds_read_b128 v[82:85], v168 offset:720
	v_add_f32_e32 v0, 1.0, v0
	v_cmp_gt_f32_e32 vcc, s33, v0
	s_waitcnt lgkmcnt(0)
	v_mov_b32_e32 v87, v82
	v_mov_b32_e32 v82, v79
	v_cndmask_b32_e64 v77, 0, 32, vcc
	v_ldexp_f32 v0, v0, v77
	v_log_f32_e32 v0, v0
	v_mov_b32_e32 v86, v78
	v_pk_mul_f32 v[78:79], v[100:101], v[82:83]
	v_mov_b32_e32 v82, v80
	v_mul_f32_e32 v77, 0x3f317217, v0
	v_fma_f32 v77, v0, s3, -v77
	v_fmac_f32_e32 v77, 0x3377d1cf, v0
	v_fmac_f32_e32 v77, 0x3f317217, v0
	v_cmp_lt_f32_e64 s[0:1], |v0|, s69
	v_pk_fma_f32 v[78:79], v[98:99], v[86:87], v[78:79]
	v_mov_b32_e32 v83, v84
	v_cndmask_b32_e64 v0, v0, v77, s[0:1]
	v_cndmask_b32_e32 v77, 0, v223, vcc
	v_sub_f32_e32 v0, v0, v77
	v_pk_fma_f32 v[78:79], v[102:103], v[82:83], v[78:79]
	v_mov_b32_e32 v84, v81
	v_sub_f32_e32 v0, v74, v0
	v_pk_fma_f32 v[78:79], v[110:111], v[84:85], v[78:79]
	v_fmamk_f32 v74, v0, 0x3d800000, v72
	v_add_f32_e32 v0, v165, v78
	v_add_f32_e32 v0, v0, v79
	ds_read_b128 v[78:81], v168 offset:736
	ds_read_b128 v[82:85], v168 offset:752
	s_waitcnt lgkmcnt(1)
	v_mov_b32_e32 v86, v78
	s_waitcnt lgkmcnt(0)
	v_mov_b32_e32 v87, v82
	v_mov_b32_e32 v82, v79
	v_pk_mul_f32 v[78:79], v[106:107], v[82:83]
	v_mov_b32_e32 v82, v80
	v_pk_fma_f32 v[78:79], v[104:105], v[86:87], v[78:79]
	v_mov_b32_e32 v83, v84
	v_pk_fma_f32 v[78:79], v[108:109], v[82:83], v[78:79]
	v_mov_b32_e32 v84, v81
	v_pk_fma_f32 v[78:79], v[112:113], v[84:85], v[78:79]
	s_nop 0
	v_add_f32_e32 v0, v0, v78
	v_add_f32_e32 v0, v0, v79
	v_min_f32_e32 v77, 0, v0
	v_mul_f32_e64 v0, |v0|, s2
	v_exp_f32_e32 v0, v0
	s_nop 0
	v_add_f32_e32 v0, 1.0, v0
	v_cmp_gt_f32_e32 vcc, s33, v0
	s_nop 1
	v_cndmask_b32_e64 v78, 0, 32, vcc
	v_ldexp_f32 v0, v0, v78
	v_log_f32_e32 v0, v0
	s_nop 0
	v_mul_f32_e32 v78, 0x3f317217, v0
	v_fma_f32 v78, v0, s3, -v78
	v_fmac_f32_e32 v78, 0x3377d1cf, v0
	v_fmac_f32_e32 v78, 0x3f317217, v0
	v_cmp_lt_f32_e64 s[0:1], |v0|, s69
	s_nop 1
	v_cndmask_b32_e64 v0, v0, v78, s[0:1]
	v_cndmask_b32_e32 v78, 0, v223, vcc
	v_sub_f32_e32 v0, v0, v78
	ds_read_b128 v[78:81], v168 offset:768
	ds_read_b128 v[82:85], v168 offset:784
	v_sub_f32_e32 v0, v77, v0
	v_fmamk_f32 v77, v0, 0x3d800000, v74
	s_waitcnt lgkmcnt(1)
	v_mov_b32_e32 v86, v78
	s_waitcnt lgkmcnt(0)
	v_mov_b32_e32 v87, v82
	v_mov_b32_e32 v82, v79
	v_pk_mul_f32 v[78:79], v[100:101], v[82:83]
	v_mov_b32_e32 v82, v80
	v_pk_fma_f32 v[78:79], v[98:99], v[86:87], v[78:79]
	v_mov_b32_e32 v83, v84
	v_pk_fma_f32 v[78:79], v[102:103], v[82:83], v[78:79]
	v_mov_b32_e32 v84, v81
	v_pk_fma_f32 v[78:79], v[110:111], v[84:85], v[78:79]
	s_nop 0
	v_add_f32_e32 v0, v165, v78
	v_add_f32_e32 v0, v0, v79
	ds_read_b128 v[78:81], v168 offset:800
	ds_read_b128 v[82:85], v168 offset:816
	s_waitcnt lgkmcnt(1)
	v_mov_b32_e32 v86, v78
	s_waitcnt lgkmcnt(0)
	v_mov_b32_e32 v87, v82
	v_mov_b32_e32 v82, v79
	v_pk_mul_f32 v[78:79], v[106:107], v[82:83]
	v_mov_b32_e32 v82, v80
	v_pk_fma_f32 v[78:79], v[104:105], v[86:87], v[78:79]
	v_mov_b32_e32 v83, v84
	v_pk_fma_f32 v[78:79], v[108:109], v[82:83], v[78:79]
	v_mov_b32_e32 v84, v81
	v_pk_fma_f32 v[78:79], v[112:113], v[84:85], v[78:79]
	ds_read_b128 v[80:83], v168 offset:832
	ds_read_b128 v[84:87], v168 offset:848
	v_add_f32_e32 v0, v0, v78
	v_add_f32_e32 v0, v0, v79
	v_min_f32_e32 v78, 0, v0
	v_mul_f32_e64 v0, |v0|, s2
	v_exp_f32_e32 v0, v0
	s_waitcnt lgkmcnt(0)
	v_mov_b32_e32 v89, v84
	v_mov_b32_e32 v84, v81
	v_mov_b32_e32 v88, v80
	v_add_f32_e32 v0, 1.0, v0
	v_cmp_gt_f32_e32 vcc, s33, v0
	v_pk_mul_f32 v[80:81], v[100:101], v[84:85]
	v_mov_b32_e32 v84, v82
	v_cndmask_b32_e64 v79, 0, 32, vcc
	v_ldexp_f32 v0, v0, v79
	v_log_f32_e32 v0, v0
	v_pk_fma_f32 v[80:81], v[98:99], v[88:89], v[80:81]
	v_mov_b32_e32 v85, v86
	v_pk_fma_f32 v[80:81], v[102:103], v[84:85], v[80:81]
	v_mul_f32_e32 v79, 0x3f317217, v0
	v_fma_f32 v79, v0, s3, -v79
	v_fmac_f32_e32 v79, 0x3377d1cf, v0
	v_fmac_f32_e32 v79, 0x3f317217, v0
	v_cmp_lt_f32_e64 s[0:1], |v0|, s69
	v_mov_b32_e32 v86, v83
	v_pk_fma_f32 v[80:81], v[110:111], v[86:87], v[80:81]
	v_cndmask_b32_e64 v0, v0, v79, s[0:1]
	v_cndmask_b32_e32 v79, 0, v223, vcc
	v_sub_f32_e32 v0, v0, v79
	v_sub_f32_e32 v0, v78, v0
	v_fmamk_f32 v78, v0, 0x3d800000, v77
	v_add_f32_e32 v0, v165, v80
	v_add_f32_e32 v0, v0, v81
	ds_read_b128 v[80:83], v168 offset:864
	ds_read_b128 v[84:87], v168 offset:880
	s_waitcnt lgkmcnt(1)
	v_mov_b32_e32 v88, v80
	s_waitcnt lgkmcnt(0)
	v_mov_b32_e32 v89, v84
	v_mov_b32_e32 v84, v81
	v_pk_mul_f32 v[80:81], v[106:107], v[84:85]
	v_mov_b32_e32 v84, v82
	v_pk_fma_f32 v[80:81], v[104:105], v[88:89], v[80:81]
	v_mov_b32_e32 v85, v86
	v_pk_fma_f32 v[80:81], v[108:109], v[84:85], v[80:81]
	v_mov_b32_e32 v86, v83
	v_pk_fma_f32 v[80:81], v[112:113], v[86:87], v[80:81]
	s_nop 0
	v_add_f32_e32 v0, v0, v80
	v_add_f32_e32 v0, v0, v81
	v_min_f32_e32 v79, 0, v0
	v_mul_f32_e64 v0, |v0|, s2
	v_exp_f32_e32 v0, v0
	s_nop 0
	v_add_f32_e32 v0, 1.0, v0
	v_cmp_gt_f32_e32 vcc, s33, v0
	s_nop 1
	v_cndmask_b32_e64 v80, 0, 32, vcc
	v_ldexp_f32 v0, v0, v80
	v_log_f32_e32 v0, v0
	s_nop 0
	v_mul_f32_e32 v80, 0x3f317217, v0
	v_fma_f32 v80, v0, s3, -v80
	v_fmac_f32_e32 v80, 0x3377d1cf, v0
	v_fmac_f32_e32 v80, 0x3f317217, v0
	v_cmp_lt_f32_e64 s[0:1], |v0|, s69
	s_nop 1
	v_cndmask_b32_e64 v0, v0, v80, s[0:1]
	v_cndmask_b32_e32 v80, 0, v223, vcc
	v_sub_f32_e32 v0, v0, v80
	ds_read_b128 v[80:83], v168 offset:896
	ds_read_b128 v[84:87], v168 offset:912
	v_sub_f32_e32 v0, v79, v0
	v_fmamk_f32 v79, v0, 0x3d800000, v78
	s_waitcnt lgkmcnt(1)
	v_mov_b32_e32 v88, v80
	s_waitcnt lgkmcnt(0)
	v_mov_b32_e32 v89, v84
	v_mov_b32_e32 v84, v81
	v_pk_mul_f32 v[80:81], v[100:101], v[84:85]
	v_mov_b32_e32 v84, v82
	v_pk_fma_f32 v[80:81], v[98:99], v[88:89], v[80:81]
	v_mov_b32_e32 v85, v86
	v_pk_fma_f32 v[80:81], v[102:103], v[84:85], v[80:81]
	v_mov_b32_e32 v86, v83
	v_pk_fma_f32 v[80:81], v[110:111], v[86:87], v[80:81]
	s_nop 0
	v_add_f32_e32 v0, v165, v80
	v_add_f32_e32 v0, v0, v81
	ds_read_b128 v[80:83], v168 offset:928
	ds_read_b128 v[84:87], v168 offset:944
	s_waitcnt lgkmcnt(1)
	v_mov_b32_e32 v88, v80
	s_waitcnt lgkmcnt(0)
	v_mov_b32_e32 v89, v84
	v_mov_b32_e32 v84, v81
	v_pk_mul_f32 v[80:81], v[106:107], v[84:85]
	v_mov_b32_e32 v84, v82
	v_pk_fma_f32 v[80:81], v[104:105], v[88:89], v[80:81]
	v_mov_b32_e32 v85, v86
	v_pk_fma_f32 v[80:81], v[108:109], v[84:85], v[80:81]
	v_mov_b32_e32 v86, v83
	v_pk_fma_f32 v[80:81], v[112:113], v[86:87], v[80:81]
	ds_read_b128 v[82:85], v168 offset:960
	ds_read_b128 v[86:89], v168 offset:976
	v_add_f32_e32 v0, v0, v80
	v_add_f32_e32 v0, v0, v81
	v_min_f32_e32 v80, 0, v0
	v_mul_f32_e64 v0, |v0|, s2
	v_exp_f32_e32 v0, v0
	s_waitcnt lgkmcnt(0)
	v_mov_b32_e32 v91, v86
	v_mov_b32_e32 v86, v83
	v_mov_b32_e32 v90, v82
	v_add_f32_e32 v0, 1.0, v0
	v_cmp_gt_f32_e32 vcc, s33, v0
	v_pk_mul_f32 v[82:83], v[100:101], v[86:87]
	v_mov_b32_e32 v86, v84
	v_cndmask_b32_e64 v81, 0, 32, vcc
	v_ldexp_f32 v0, v0, v81
	v_log_f32_e32 v0, v0
	v_pk_fma_f32 v[82:83], v[98:99], v[90:91], v[82:83]
	v_mov_b32_e32 v87, v88
	v_pk_fma_f32 v[82:83], v[102:103], v[86:87], v[82:83]
	v_mul_f32_e32 v81, 0x3f317217, v0
	v_fma_f32 v81, v0, s3, -v81
	v_fmac_f32_e32 v81, 0x3377d1cf, v0
	v_fmac_f32_e32 v81, 0x3f317217, v0
	v_cmp_lt_f32_e64 s[0:1], |v0|, s69
	v_mov_b32_e32 v88, v85
	v_pk_fma_f32 v[82:83], v[110:111], v[88:89], v[82:83]
	v_cndmask_b32_e64 v0, v0, v81, s[0:1]
	v_cndmask_b32_e32 v81, 0, v223, vcc
	v_sub_f32_e32 v0, v0, v81
	v_sub_f32_e32 v0, v80, v0
	v_fmamk_f32 v81, v0, 0x3d800000, v79
	v_add_f32_e32 v0, v165, v82
	v_add_f32_e32 v0, v0, v83
	ds_read_b128 v[82:85], v168 offset:992
	ds_read_b128 v[86:89], v168 offset:1008
	s_waitcnt lgkmcnt(1)
	v_mov_b32_e32 v90, v82
	s_waitcnt lgkmcnt(0)
	v_mov_b32_e32 v91, v86
	v_mov_b32_e32 v86, v83
	v_pk_mul_f32 v[82:83], v[106:107], v[86:87]
	v_mov_b32_e32 v86, v84
	v_pk_fma_f32 v[82:83], v[104:105], v[90:91], v[82:83]
	v_mov_b32_e32 v87, v88
	v_pk_fma_f32 v[82:83], v[108:109], v[86:87], v[82:83]
	v_mov_b32_e32 v88, v85
	v_pk_fma_f32 v[82:83], v[112:113], v[88:89], v[82:83]
	s_nop 0
	v_add_f32_e32 v0, v0, v82
	v_add_f32_e32 v0, v0, v83
	v_min_f32_e32 v80, 0, v0
	v_mul_f32_e64 v0, |v0|, s2
	v_exp_f32_e32 v0, v0
	s_nop 0
	v_add_f32_e32 v0, 1.0, v0
	v_cmp_gt_f32_e32 vcc, s33, v0
	s_nop 1
	v_cndmask_b32_e64 v82, 0, 32, vcc
	v_ldexp_f32 v0, v0, v82
	v_log_f32_e32 v0, v0
	s_nop 0
	v_mul_f32_e32 v82, 0x3f317217, v0
	v_fma_f32 v82, v0, s3, -v82
	v_fmac_f32_e32 v82, 0x3377d1cf, v0
	v_fmac_f32_e32 v82, 0x3f317217, v0
	v_cmp_lt_f32_e64 s[0:1], |v0|, s69
	s_nop 1
	v_cndmask_b32_e64 v0, v0, v82, s[0:1]
	v_cndmask_b32_e32 v82, 0, v223, vcc
	v_sub_f32_e32 v0, v0, v82
	v_sub_f32_e32 v0, v80, v0
	v_fmamk_f32 v82, v0, 0x3d800000, v81
	ds_write_b32 v169, v82 offset:4096
	s_waitcnt lgkmcnt(0)
	s_barrier
	v_add_u32_e32 v90, s62, v171
	v_ashrrev_i32_e32 v91, 31, v90
	v_lshlrev_b64 v[90:91], 11, v[90:91]
	v_lshl_add_u64 v[90:91], v[114:115], 0, v[90:91]
	global_load_ushort v128, v[90:91], off
	global_load_ushort v144, v[90:91], off offset:1024
	v_or_b32_e32 v92, 1, v171
	v_add_u32_e32 v92, s62, v92
	v_ashrrev_i32_e32 v93, 31, v92
	v_lshlrev_b64 v[92:93], 11, v[92:93]
	v_lshl_add_u64 v[92:93], v[114:115], 0, v[92:93]
	global_load_ushort v129, v[92:93], off
	global_load_ushort v145, v[92:93], off offset:1024
	v_or_b32_e32 v90, 2, v171
	v_add_u32_e32 v90, s62, v90
	v_ashrrev_i32_e32 v91, 31, v90
	v_lshlrev_b64 v[90:91], 11, v[90:91]
	v_lshl_add_u64 v[90:91], v[114:115], 0, v[90:91]
	global_load_ushort v130, v[90:91], off
	global_load_ushort v146, v[90:91], off offset:1024
	v_or_b32_e32 v92, 3, v171
	v_add_u32_e32 v92, s62, v92
	v_ashrrev_i32_e32 v93, 31, v92
	v_lshlrev_b64 v[92:93], 11, v[92:93]
	v_lshl_add_u64 v[92:93], v[114:115], 0, v[92:93]
	global_load_ushort v131, v[92:93], off
	global_load_ushort v147, v[92:93], off offset:1024
	v_or_b32_e32 v90, 4, v171
	v_add_u32_e32 v90, s62, v90
	v_ashrrev_i32_e32 v91, 31, v90
	v_lshlrev_b64 v[90:91], 11, v[90:91]
	v_lshl_add_u64 v[90:91], v[114:115], 0, v[90:91]
	global_load_ushort v132, v[90:91], off
	global_load_ushort v148, v[90:91], off offset:1024
	v_or_b32_e32 v92, 5, v171
	v_add_u32_e32 v92, s62, v92
	v_ashrrev_i32_e32 v93, 31, v92
	v_lshlrev_b64 v[92:93], 11, v[92:93]
	v_lshl_add_u64 v[92:93], v[114:115], 0, v[92:93]
	global_load_ushort v133, v[92:93], off
	global_load_ushort v149, v[92:93], off offset:1024
	v_or_b32_e32 v90, 6, v171
	v_add_u32_e32 v90, s62, v90
	v_ashrrev_i32_e32 v91, 31, v90
	v_lshlrev_b64 v[90:91], 11, v[90:91]
	v_lshl_add_u64 v[90:91], v[114:115], 0, v[90:91]
	global_load_ushort v134, v[90:91], off
	global_load_ushort v150, v[90:91], off offset:1024
	v_or_b32_e32 v92, 7, v171
	v_add_u32_e32 v92, s62, v92
	v_ashrrev_i32_e32 v93, 31, v92
	v_lshlrev_b64 v[92:93], 11, v[92:93]
	v_lshl_add_u64 v[92:93], v[114:115], 0, v[92:93]
	global_load_ushort v135, v[92:93], off
	global_load_ushort v151, v[92:93], off offset:1024
	v_or_b32_e32 v90, 8, v171
	v_add_u32_e32 v90, s62, v90
	v_ashrrev_i32_e32 v91, 31, v90
	v_lshlrev_b64 v[90:91], 11, v[90:91]
	v_lshl_add_u64 v[90:91], v[114:115], 0, v[90:91]
	global_load_ushort v136, v[90:91], off
	global_load_ushort v152, v[90:91], off offset:1024
	v_or_b32_e32 v92, 9, v171
	v_add_u32_e32 v92, s62, v92
	v_ashrrev_i32_e32 v93, 31, v92
	v_lshlrev_b64 v[92:93], 11, v[92:93]
	v_lshl_add_u64 v[92:93], v[114:115], 0, v[92:93]
	global_load_ushort v137, v[92:93], off
	global_load_ushort v153, v[92:93], off offset:1024
	v_or_b32_e32 v90, 10, v171
	v_add_u32_e32 v90, s62, v90
	v_ashrrev_i32_e32 v91, 31, v90
	v_lshlrev_b64 v[90:91], 11, v[90:91]
	v_lshl_add_u64 v[90:91], v[114:115], 0, v[90:91]
	global_load_ushort v138, v[90:91], off
	global_load_ushort v154, v[90:91], off offset:1024
	v_or_b32_e32 v92, 11, v171
	v_add_u32_e32 v92, s62, v92
	v_ashrrev_i32_e32 v93, 31, v92
	v_lshlrev_b64 v[92:93], 11, v[92:93]
	v_lshl_add_u64 v[92:93], v[114:115], 0, v[92:93]
	global_load_ushort v139, v[92:93], off
	global_load_ushort v155, v[92:93], off offset:1024
	v_or_b32_e32 v90, 12, v171
	v_add_u32_e32 v90, s62, v90
	v_ashrrev_i32_e32 v91, 31, v90
	v_lshlrev_b64 v[90:91], 11, v[90:91]
	v_lshl_add_u64 v[90:91], v[114:115], 0, v[90:91]
	global_load_ushort v140, v[90:91], off
	global_load_ushort v156, v[90:91], off offset:1024
	v_or_b32_e32 v92, 13, v171
	v_add_u32_e32 v92, s62, v92
	v_ashrrev_i32_e32 v93, 31, v92
	v_lshlrev_b64 v[92:93], 11, v[92:93]
	v_lshl_add_u64 v[92:93], v[114:115], 0, v[92:93]
	global_load_ushort v141, v[92:93], off
	global_load_ushort v157, v[92:93], off offset:1024
	v_or_b32_e32 v90, 14, v171
	v_add_u32_e32 v90, s62, v90
	v_ashrrev_i32_e32 v91, 31, v90
	v_lshlrev_b64 v[90:91], 11, v[90:91]
	v_lshl_add_u64 v[90:91], v[114:115], 0, v[90:91]
	global_load_ushort v142, v[90:91], off
	global_load_ushort v158, v[90:91], off offset:1024
	v_or_b32_e32 v92, 15, v171
	v_add_u32_e32 v92, s62, v92
	v_ashrrev_i32_e32 v93, 31, v92
	v_lshlrev_b64 v[92:93], 11, v[92:93]
	v_lshl_add_u64 v[92:93], v[114:115], 0, v[92:93]
	global_load_ushort v143, v[92:93], off
	global_load_ushort v159, v[92:93], off offset:1024
	ds_read2st64_b32 v[84:85], v170 offset0:16 offset1:18
	s_waitcnt lgkmcnt(0)
	v_add_f32_e32 v0, 0, v84
	v_cndmask_b32_e64 v80, 0, v0, s[14:15]
	v_add_f32_e32 v0, v0, v85
	v_add_f32_e32 v83, v85, v80
	ds_read2st64_b32 v[84:85], v170 offset0:20 offset1:22
	v_cndmask_b32_e64 v80, v80, v83, s[16:17]
	s_waitcnt lgkmcnt(0)
	v_add_f32_e32 v83, v84, v80
	v_add_f32_e32 v0, v0, v84
	v_cndmask_b32_e64 v83, v80, v83, s[18:19]
	v_add_u32_e32 v84, s62, v171
	v_add_f32_e32 v80, v0, v85
	v_add_f32_e32 v0, v85, v83
	v_ashrrev_i32_e32 v85, 31, v84
	v_lshlrev_b64 v[84:85], 11, v[84:85]
	v_lshl_add_u64 v[84:85], v[114:115], 0, v[84:85]
	v_mov_b32_e32 v86, v128
	v_cndmask_b32_e64 v83, v83, v0, s[20:21]
	v_add_f32_e32 v66, v66, v83
	v_mul_f32_e32 v66, 0xbfb8aa3b, v66
	v_exp_f32_e32 v66, v66
	v_add_f32_e32 v67, v67, v83
	v_mul_f32_e32 v67, 0xbfb8aa3b, v67
	v_exp_f32_e32 v67, v67
	v_rcp_f32_e32 v87, v66
	v_mul_f32_e32 v0, 0x3fb8aa3b, v80
	v_exp_f32_e32 v0, v0
	v_add_f32_e32 v70, v70, v83
	v_mul_f32_e32 v70, 0xbfb8aa3b, v70
	v_exp_f32_e32 v70, v70
	v_add_f32_e32 v71, v71, v83
	v_mul_f32_e32 v71, 0xbfb8aa3b, v71
	v_exp_f32_e32 v71, v71
	s_waitcnt vmcnt(0)
	v_lshlrev_b32_e32 v86, 16, v86
	v_mul_f32_e32 v86, 0x3db504f3, v86
	v_mul_f32_e32 v86, v86, v87
	v_cvt_pk_bf16_f32 v86, v86, s0
	ds_write_b16 v177, v86 offset:8704
	v_add_u32_e32 v86, s62, v178
	v_ashrrev_i32_e32 v87, 31, v86
	v_lshlrev_b64 v[86:87], 11, v[86:87]
	v_lshl_add_u64 v[86:87], v[114:115], 0, v[86:87]
	v_mov_b32_e32 v84, v144
	s_nop 0
	v_mov_b32_e32 v85, v145
	s_waitcnt vmcnt(1)
	v_lshlrev_b32_e32 v84, 16, v84
	s_waitcnt vmcnt(0)
	v_lshlrev_b32_e32 v85, 16, v85
	v_pk_mul_f32 v[84:85], v[66:67], v[84:85]
	v_rcp_f32_e32 v67, v67
	v_cvt_pk_bf16_f32 v66, v84, s0
	ds_write_b16 v177, v66 offset:26112
	v_mov_b32_e32 v66, v129
	v_pk_mul_f32 v[88:89], v[0:1], v[84:85] op_sel_hi:[0,1]
	s_waitcnt vmcnt(0)
	v_lshlrev_b32_e32 v66, 16, v66
	v_mul_f32_e32 v66, 0x3db504f3, v66
	v_mul_f32_e32 v66, v67, v66
	v_add_f32_e32 v67, v68, v83
	v_or_b32_e32 v68, 2, v171
	v_cvt_pk_bf16_f32 v66, v66, s0
	v_add_u32_e32 v84, s62, v68
	ds_write_b16 v179, v66 offset:8704
	v_cvt_pk_bf16_f32 v66, v85, s0
	v_ashrrev_i32_e32 v85, 31, v84
	v_lshlrev_b64 v[84:85], 11, v[84:85]
	v_lshl_add_u64 v[84:85], v[114:115], 0, v[84:85]
	v_mul_f32_e32 v67, 0xbfb8aa3b, v67
	v_exp_f32_e32 v68, v67
	v_mov_b32_e32 v67, v130
	ds_write_b16 v179, v66 offset:26112
	v_cvt_pk_bf16_f32 v66, v88, v89
	v_rcp_f32_e32 v86, v68
	s_waitcnt vmcnt(0)
	v_lshlrev_b32_e32 v67, 16, v67
	v_mul_f32_e32 v67, 0x3db504f3, v67
	v_mul_f32_e32 v67, v86, v67
	v_cvt_pk_bf16_f32 v67, v67, s0
	ds_write_b16 v180, v67 offset:8704
	v_add_f32_e32 v67, v69, v83
	v_or_b32_e32 v69, 3, v171
	v_add_u32_e32 v86, s62, v69
	v_ashrrev_i32_e32 v87, 31, v86
	v_lshlrev_b64 v[86:87], 11, v[86:87]
	v_mul_f32_e32 v67, 0xbfb8aa3b, v67
	v_lshl_add_u64 v[86:87], v[114:115], 0, v[86:87]
	v_exp_f32_e32 v69, v67
	v_mov_b32_e32 v67, v146
	s_nop 0
	v_mov_b32_e32 v84, v147
	s_waitcnt vmcnt(0)
	v_lshlrev_b32_e32 v85, 16, v84
	v_lshlrev_b32_e32 v84, 16, v67
	v_pk_mul_f32 v[84:85], v[68:69], v[84:85]
	v_rcp_f32_e32 v68, v69
	v_cvt_pk_bf16_f32 v67, v84, s0
	ds_write_b16 v180, v67 offset:26112
	v_mov_b32_e32 v67, v131
	v_pk_mul_f32 v[88:89], v[0:1], v[84:85] op_sel_hi:[0,1]
	s_waitcnt vmcnt(0)
	v_lshlrev_b32_e32 v67, 16, v67
	v_mul_f32_e32 v67, 0x3db504f3, v67
	v_mul_f32_e32 v67, v68, v67
	v_or_b32_e32 v68, 4, v171
	v_add_u32_e32 v68, s62, v68
	v_ashrrev_i32_e32 v69, 31, v68
	v_lshlrev_b64 v[68:69], 11, v[68:69]
	v_lshl_add_u64 v[68:69], v[114:115], 0, v[68:69]
	v_mov_b32_e32 v84, v132
	v_cvt_pk_bf16_f32 v67, v67, s0
	ds_write_b16 v181, v67 offset:8704
	v_cvt_pk_bf16_f32 v67, v85, s0
	v_rcp_f32_e32 v85, v70
	ds_write_b16 v181, v67 offset:26112
	v_cvt_pk_bf16_f32 v67, v88, v89
	s_waitcnt vmcnt(0)
	v_lshlrev_b32_e32 v84, 16, v84
	v_mul_f32_e32 v84, 0x3db504f3, v84
	v_mul_f32_e32 v84, v85, v84
	v_cvt_pk_bf16_f32 v84, v84, s0
	ds_write_b16 v182, v84 offset:8704
	v_or_b32_e32 v84, 5, v171
	v_add_u32_e32 v84, s62, v84
	v_ashrrev_i32_e32 v85, 31, v84
	v_lshlrev_b64 v[84:85], 11, v[84:85]
	v_lshl_add_u64 v[84:85], v[114:115], 0, v[84:85]
	v_mov_b32_e32 v68, v148
	s_nop 0
	v_mov_b32_e32 v69, v149
	s_waitcnt vmcnt(1)
	v_lshlrev_b32_e32 v68, 16, v68
	s_waitcnt vmcnt(0)
	v_lshlrev_b32_e32 v69, 16, v69
	v_pk_mul_f32 v[68:69], v[70:71], v[68:69]
	s_nop 0
	v_cvt_pk_bf16_f32 v70, v68, s0
	v_pk_mul_f32 v[86:87], v[0:1], v[68:69] op_sel_hi:[0,1]
	v_mov_b32_e32 v68, v133
	ds_write_b16 v182, v70 offset:26112
	v_rcp_f32_e32 v70, v71
	s_waitcnt vmcnt(0)
	v_lshlrev_b32_e32 v68, 16, v68
	v_mul_f32_e32 v68, 0x3db504f3, v68
	v_mul_f32_e32 v68, v70, v68
	v_or_b32_e32 v70, 6, v171
	v_add_u32_e32 v70, s62, v70
	v_cvt_pk_bf16_f32 v68, v68, s0
	v_ashrrev_i32_e32 v71, 31, v70
	ds_write_b16 v183, v68 offset:8704
	v_cvt_pk_bf16_f32 v68, v69, s0
	v_add_f32_e32 v69, v73, v83
	v_lshlrev_b64 v[70:71], 11, v[70:71]
	v_lshl_add_u64 v[70:71], v[114:115], 0, v[70:71]
	v_mul_f32_e32 v69, 0xbfb8aa3b, v69
	v_exp_f32_e32 v84, v69
	v_mov_b32_e32 v69, v134
	ds_write_b16 v183, v68 offset:26112
	v_cvt_pk_bf16_f32 v68, v86, v87
	v_rcp_f32_e32 v73, v84
	s_waitcnt vmcnt(0)
	v_lshlrev_b32_e32 v69, 16, v69
	v_mul_f32_e32 v69, 0x3db504f3, v69
	v_mul_f32_e32 v69, v73, v69
	v_or_b32_e32 v73, 7, v171
	v_cvt_pk_bf16_f32 v69, v69, s0
	v_add_u32_e32 v86, s62, v73
	ds_write_b16 v184, v69 offset:8704
	v_add_f32_e32 v69, v75, v83
	v_ashrrev_i32_e32 v87, 31, v86
	v_lshlrev_b64 v[86:87], 11, v[86:87]
	v_mul_f32_e32 v69, 0xbfb8aa3b, v69
	v_lshl_add_u64 v[86:87], v[114:115], 0, v[86:87]
	v_exp_f32_e32 v85, v69
	v_mov_b32_e32 v69, v150
	s_nop 0
	v_mov_b32_e32 v71, v151
	v_add_f32_e32 v73, v76, v83
	v_mul_f32_e32 v73, 0xbfb8aa3b, v73
	s_waitcnt vmcnt(1)
	v_lshlrev_b32_e32 v70, 16, v69
	s_waitcnt vmcnt(0)
	v_lshlrev_b32_e32 v71, 16, v71
	v_pk_mul_f32 v[70:71], v[84:85], v[70:71]
	v_exp_f32_e32 v84, v73
	v_cvt_pk_bf16_f32 v69, v70, s0
	ds_write_b16 v184, v69 offset:26112
	v_mov_b32_e32 v69, v135
	v_pk_mul_f32 v[88:89], v[0:1], v[70:71] op_sel_hi:[0,1]
	v_rcp_f32_e32 v70, v85
	v_rcp_f32_e32 v75, v84
	s_waitcnt vmcnt(0)
	v_lshlrev_b32_e32 v69, 16, v69
	v_mul_f32_e32 v69, 0x3db504f3, v69
	v_mul_f32_e32 v69, v70, v69
	v_or_b32_e32 v70, 8, v171
	v_cvt_pk_bf16_f32 v69, v69, s0
	v_add_u32_e32 v70, s62, v70
	ds_write_b16 v185, v69 offset:8704
	v_cvt_pk_bf16_f32 v69, v71, s0
	v_ashrrev_i32_e32 v71, 31, v70
	v_lshlrev_b64 v[70:71], 11, v[70:71]
	v_lshl_add_u64 v[70:71], v[114:115], 0, v[70:71]
	v_mov_b32_e32 v73, v136
	ds_write_b16 v185, v69 offset:26112
	v_cvt_pk_bf16_f32 v69, v88, v89
	s_waitcnt vmcnt(0)
	v_lshlrev_b32_e32 v73, 16, v73
	v_mul_f32_e32 v73, 0x3db504f3, v73
	v_mul_f32_e32 v73, v75, v73
	v_add_f32_e32 v75, v72, v83
	v_or_b32_e32 v72, 9, v171
	v_cvt_pk_bf16_f32 v73, v73, s0
	v_add_u32_e32 v72, s62, v72
	ds_write_b16 v186, v73 offset:8704
	v_ashrrev_i32_e32 v73, 31, v72
	v_lshlrev_b64 v[72:73], 11, v[72:73]
	v_lshl_add_u64 v[72:73], v[114:115], 0, v[72:73]
	v_mov_b32_e32 v70, v152
	s_nop 0
	v_mov_b32_e32 v71, v153
	v_mul_f32_e32 v75, 0xbfb8aa3b, v75
	v_exp_f32_e32 v85, v75
	s_waitcnt vmcnt(1)
	v_lshlrev_b32_e32 v70, 16, v70
	s_waitcnt vmcnt(0)
	v_lshlrev_b32_e32 v71, 16, v71
	v_pk_mul_f32 v[70:71], v[84:85], v[70:71]
	s_nop 0
	v_cvt_pk_bf16_f32 v75, v70, s0
	v_pk_mul_f32 v[86:87], v[0:1], v[70:71] op_sel_hi:[0,1]
	v_mov_b32_e32 v70, v137
	v_rcp_f32_e32 v72, v85
	ds_write_b16 v186, v75 offset:26112
	s_waitcnt vmcnt(0)
	v_lshlrev_b32_e32 v70, 16, v70
	v_mul_f32_e32 v70, 0x3db504f3, v70
	v_mul_f32_e32 v70, v72, v70
	v_or_b32_e32 v72, 10, v171
	v_add_u32_e32 v72, s62, v72
	v_cvt_pk_bf16_f32 v70, v70, s0
	v_ashrrev_i32_e32 v73, 31, v72
	ds_write_b16 v187, v70 offset:8704
	v_cvt_pk_bf16_f32 v70, v71, s0
	v_add_f32_e32 v71, v74, v83
	v_lshlrev_b64 v[72:73], 11, v[72:73]
	v_lshl_add_u64 v[72:73], v[114:115], 0, v[72:73]
	v_mul_f32_e32 v71, 0xbfb8aa3b, v71
	v_exp_f32_e32 v74, v71
	v_mov_b32_e32 v71, v138
	ds_write_b16 v187, v70 offset:26112
	v_cvt_pk_bf16_f32 v70, v86, v87
	v_rcp_f32_e32 v75, v74
	s_waitcnt vmcnt(0)
	v_lshlrev_b32_e32 v71, 16, v71
	v_mul_f32_e32 v71, 0x3db504f3, v71
	v_mul_f32_e32 v71, v75, v71
	v_or_b32_e32 v75, 11, v171
	v_cvt_pk_bf16_f32 v71, v71, s0
	v_add_u32_e32 v76, s62, v75
	ds_write_b16 v188, v71 offset:8704
	v_add_f32_e32 v71, v77, v83
	v_ashrrev_i32_e32 v77, 31, v76
	v_lshlrev_b64 v[76:77], 11, v[76:77]
	v_mul_f32_e32 v71, 0xbfb8aa3b, v71
	v_lshl_add_u64 v[76:77], v[114:115], 0, v[76:77]
	v_exp_f32_e32 v75, v71
	v_mov_b32_e32 v71, v154
	s_nop 0
	v_mov_b32_e32 v73, v155
	s_waitcnt vmcnt(1)
	v_lshlrev_b32_e32 v72, 16, v71
	s_waitcnt vmcnt(0)
	v_lshlrev_b32_e32 v73, 16, v73
	v_pk_mul_f32 v[72:73], v[74:75], v[72:73]
	v_add_f32_e32 v74, v78, v83
	v_cvt_pk_bf16_f32 v71, v72, s0
	ds_write_b16 v188, v71 offset:26112
	v_mov_b32_e32 v71, v139
	v_pk_mul_f32 v[84:85], v[0:1], v[72:73] op_sel_hi:[0,1]
	v_rcp_f32_e32 v72, v75
	v_mul_f32_e32 v74, 0xbfb8aa3b, v74
	v_exp_f32_e32 v74, v74
	v_rcp_f32_e32 v76, v74
	s_waitcnt vmcnt(0)
	v_lshlrev_b32_e32 v71, 16, v71
	v_mul_f32_e32 v71, 0x3db504f3, v71
	v_mul_f32_e32 v71, v72, v71
	v_or_b32_e32 v72, 12, v171
	v_cvt_pk_bf16_f32 v71, v71, s0
	v_add_u32_e32 v72, s62, v72
	ds_write_b16 v189, v71 offset:8704
	v_cvt_pk_bf16_f32 v71, v73, s0
	v_ashrrev_i32_e32 v73, 31, v72
	v_lshlrev_b64 v[72:73], 11, v[72:73]
	v_lshl_add_u64 v[72:73], v[114:115], 0, v[72:73]
	v_mov_b32_e32 v75, v140
	ds_write_b16 v189, v71 offset:26112
	v_cvt_pk_bf16_f32 v71, v84, v85
	s_waitcnt vmcnt(0)
	v_lshlrev_b32_e32 v75, 16, v75
	v_mul_f32_e32 v75, 0x3db504f3, v75
	v_mul_f32_e32 v75, v76, v75
	v_or_b32_e32 v76, 13, v171
	v_add_u32_e32 v76, s62, v76
	v_cvt_pk_bf16_f32 v75, v75, s0
	v_ashrrev_i32_e32 v77, 31, v76
	ds_write_b16 v190, v75 offset:8704
	v_lshlrev_b64 v[76:77], 11, v[76:77]
	v_lshl_add_u64 v[76:77], v[114:115], 0, v[76:77]
	v_mov_b32_e32 v72, v156
	s_nop 0
	v_mov_b32_e32 v73, v157
	v_add_f32_e32 v75, v79, v83
	v_mul_f32_e32 v75, 0xbfb8aa3b, v75
	v_exp_f32_e32 v75, v75
	s_waitcnt vmcnt(1)
	v_lshlrev_b32_e32 v72, 16, v72
	s_waitcnt vmcnt(0)
	v_lshlrev_b32_e32 v73, 16, v73
	v_pk_mul_f32 v[72:73], v[74:75], v[72:73]
	s_nop 0
	v_cvt_pk_bf16_f32 v74, v72, s0
	v_pk_mul_f32 v[78:79], v[0:1], v[72:73] op_sel_hi:[0,1]
	v_mov_b32_e32 v72, v141
	ds_write_b16 v190, v74 offset:26112
	v_rcp_f32_e32 v74, v75
	s_waitcnt vmcnt(0)
	v_lshlrev_b32_e32 v72, 16, v72
	v_mul_f32_e32 v72, 0x3db504f3, v72
	v_mul_f32_e32 v72, v74, v72
	v_or_b32_e32 v74, 14, v171
	v_add_u32_e32 v74, s62, v74
	v_cvt_pk_bf16_f32 v72, v72, s0
	v_ashrrev_i32_e32 v75, 31, v74
	ds_write_b16 v191, v72 offset:8704
	v_cvt_pk_bf16_f32 v72, v73, s0
	v_add_f32_e32 v73, v81, v83
	v_lshlrev_b64 v[74:75], 11, v[74:75]
	v_lshl_add_u64 v[76:77], v[114:115], 0, v[74:75]
	v_mul_f32_e32 v73, 0xbfb8aa3b, v73
	v_exp_f32_e32 v74, v73
	v_mov_b32_e32 v73, v142
	ds_write_b16 v191, v72 offset:26112
	v_cvt_pk_bf16_f32 v72, v78, v79
	v_rcp_f32_e32 v75, v74
	s_waitcnt vmcnt(0)
	v_lshlrev_b32_e32 v73, 16, v73
	v_mul_f32_e32 v73, 0x3db504f3, v73
	v_mul_f32_e32 v73, v75, v73
	v_or_b32_e32 v75, 15, v171
	v_cvt_pk_bf16_f32 v73, v73, s0
	v_add_u32_e32 v78, s62, v75
	ds_write_b16 v192, v73 offset:8704
	v_add_f32_e32 v73, v83, v82
	v_ashrrev_i32_e32 v79, 31, v78
	v_lshlrev_b64 v[78:79], 11, v[78:79]
	v_mul_f32_e32 v73, 0xbfb8aa3b, v73
	v_lshl_add_u64 v[82:83], v[114:115], 0, v[78:79]
	v_exp_f32_e32 v75, v73
	v_mov_b32_e32 v73, v158
	s_nop 0
	v_mov_b32_e32 v77, v159
	s_waitcnt vmcnt(1)
	v_lshlrev_b32_e32 v76, 16, v73
	s_waitcnt vmcnt(0)
	v_lshlrev_b32_e32 v77, 16, v77
	v_pk_mul_f32 v[76:77], v[74:75], v[76:77]
	s_nop 0
	v_pk_mul_f32 v[78:79], v[0:1], v[76:77] op_sel_hi:[0,1]
	v_mov_b32_e32 v0, v143
	v_cvt_pk_bf16_f32 v73, v76, s0
	ds_write_b16 v192, v73 offset:26112
	v_rcp_f32_e32 v73, v75
	s_waitcnt vmcnt(0)
	v_lshlrev_b32_e32 v0, 16, v0
	v_mul_f32_e32 v0, 0x3db504f3, v0
	v_mul_f32_e32 v0, v73, v0
	v_cvt_pk_bf16_f32 v0, v0, s0
	ds_write_b16 v193, v0 offset:8704
	v_cvt_pk_bf16_f32 v0, v77, s0
	ds_write_b16 v193, v0 offset:26112
	v_cvt_pk_bf16_f32 v73, v78, v79
	ds_write_b128 v210, v[66:69] offset:43520
	ds_write_b128 v210, v[70:73] offset:43536
	s_and_saveexec_b64 s[0:1], s[10:11]
	ds_write_b32 v170, v80 offset:6144
	s_or_b64 exec, exec, s[0:1]
	v_or_b32_e32 v66, s62, v164
	v_ashrrev_i32_e32 v67, 31, v66
	v_lshlrev_b64 v[66:67], 11, v[66:67]
	v_lshl_add_u64 v[70:71], s[48:49], 0, v[66:67]
	v_lshl_add_u64 v[66:67], v[120:121], 1, v[70:71]
	global_load_dwordx4 v[66:69], v[66:67], off
	s_andn2_b64 vcc, exec, s[50:51]
	v_add_u32_e32 v0, s58, v174
	s_waitcnt vmcnt(0)
	ds_write_b16 v211, v66 offset:61952
	ds_write_b16_d16_hi v211, v66 offset:62096
	ds_write_b16 v211, v67 offset:62240
	ds_write_b16_d16_hi v211, v67 offset:62384
	ds_write_b16 v211, v68 offset:62528
	ds_write_b16_d16_hi v211, v68 offset:62672
	ds_write_b16 v211, v69 offset:62816
	ds_write_b16_d16_hi v211, v69 offset:62960
	v_lshl_add_u64 v[66:67], v[122:123], 1, v[70:71]
	global_load_dwordx4 v[66:69], v[66:67], off
	s_waitcnt vmcnt(0)
	ds_write_b16 v212, v66 offset:61952
	ds_write_b16_d16_hi v212, v66 offset:62096
	ds_write_b16 v212, v67 offset:62240
	ds_write_b16_d16_hi v212, v67 offset:62384
	ds_write_b16 v212, v68 offset:62528
	ds_write_b16_d16_hi v212, v68 offset:62672
	ds_write_b16 v212, v69 offset:62816
	ds_write_b16_d16_hi v212, v69 offset:62960
	v_lshl_add_u64 v[66:67], v[124:125], 1, v[70:71]
	global_load_dwordx4 v[66:69], v[66:67], off
	s_waitcnt vmcnt(0)
	ds_write_b16 v213, v66 offset:61952
	ds_write_b16_d16_hi v213, v66 offset:62096
	ds_write_b16 v213, v67 offset:62240
	ds_write_b16_d16_hi v213, v67 offset:62384
	ds_write_b16 v213, v68 offset:62528
	ds_write_b16_d16_hi v213, v68 offset:62672
	ds_write_b16 v213, v69 offset:62816
	ds_write_b16_d16_hi v213, v69 offset:62960
	v_lshl_add_u64 v[66:67], v[126:127], 1, v[70:71]
	global_load_dwordx4 v[66:69], v[66:67], off
	s_waitcnt vmcnt(0)
	ds_write_b16 v214, v66 offset:61952
	ds_write_b16_d16_hi v214, v66 offset:62096
	ds_write_b16 v214, v67 offset:62240
	ds_write_b16_d16_hi v214, v67 offset:62384
	ds_write_b16 v214, v68 offset:62528
	ds_write_b16_d16_hi v214, v68 offset:62672
	ds_write_b16 v214, v69 offset:62816
	ds_write_b16_d16_hi v214, v69 offset:62960
	v_mov_b32_e32 v66, 0
	v_mov_b32_e32 v67, 0
	v_mov_b32_e32 v68, 0
	v_mov_b32_e32 v69, 0
	s_waitcnt lgkmcnt(0)
	s_barrier
	s_cbranch_vccnz .LBB0_46
	ds_read_b128 v[66:69], v0 offset:26112
	ds_read_b128 v[70:73], v244 offset:8704
	s_waitcnt lgkmcnt(0)
	v_mfma_f32_16x16x32_bf16 v[66:69], v[66:69], v[70:73], 0
	ds_read_b128 v[70:73], v0 offset:26176
	ds_read_b128 v[74:77], v244 offset:8768
	s_waitcnt lgkmcnt(0)
	v_mfma_f32_16x16x32_bf16 v[66:69], v[70:73], v[74:77], v[66:69]
	ds_read_b128 v[70:73], v0 offset:26240
	ds_read_b128 v[74:77], v244 offset:8832
	s_waitcnt lgkmcnt(0)
	v_mfma_f32_16x16x32_bf16 v[66:69], v[70:73], v[74:77], v[66:69]
	ds_read_b128 v[70:73], v0 offset:26304
	ds_read_b128 v[74:77], v244 offset:8896
	s_waitcnt lgkmcnt(0)
	v_mfma_f32_16x16x32_bf16 v[66:69], v[70:73], v[74:77], v[66:69]
